# up-GEMM epilogue: conv weights for columns 0-3 loaded first and waited separately (vmcnt 24 then 16)
# speedup vs baseline: 1.0071x; 1.0021x over previous
; __device__ __forceinline__ unsigned cvt_pk_bf16(float lo, float hi) { unsigned r; asm volatile("v_cvt_pk_bf16_f32 %0, %1, %2" : "=v"(r) : "v"(lo), "v"(hi)); return r; }
;     __device__ __forceinline__ void operator()(f32x4 (&acc)[2][2][4][2], const Unit& u, int wr, int wc, int fr, int fq, const LAS float* rtab) const {
;     ...
;             for (int m = 0; m < 4; ++m) { const float r = rtab[ai * HALF + wr * 64 + m * 16 + fr];
; #pragma unroll
;                 for (int bj = 0; bj < 2; ++bj)
; #pragma unroll
;                     for (int n = 0; n < 2; ++n) acc[ai][bj][m][n] = acc[ai][bj][m][n] * r; }
; #pragma unroll
;         for (int ai = 0; ai < 2; ++ai) {
;             const int blk = (u.pm * BM + ai * HALF + wr * 64) >> 6;
;             if (fr < 2) { bf16_t* rp = raw + ((size_t)blk * 4 + fr) * UP_N + c0;
;                 const f32x4 g0 = acc[ai][0][0][0], g1 = acc[ai][0][0][1], u0 = acc[ai][1][0][0], u1 = acc[ai][1][0][1];
;                 u32x4 w; w.x = cvt_pk_bf16(g0[0], g0[1]); w.y = cvt_pk_bf16(g0[2], g0[3]); w.z = cvt_pk_bf16(g1[0], g1[1]); w.w = cvt_pk_bf16(g1[2], g1[3]); *(u32x4*)rp = w;
;                 w.x = cvt_pk_bf16(u0[0], u0[1]); w.y = cvt_pk_bf16(u0[2], u0[3]); w.z = cvt_pk_bf16(u1[0], u1[1]); w.w = cvt_pk_bf16(u1[2], u1[3]); *(u32x4*)(rp + DFF) = w; }
;             if (fr >= 14) { bf16_t* rp = raw + ((size_t)blk * 4 + (fr - 12)) * UP_N + c0;
;                 const f32x4 g0 = acc[ai][0][3][0], g1 = acc[ai][0][3][1], u0 = acc[ai][1][3][0], u1 = acc[ai][1][3][1];
;                 u32x4 w; w.x = cvt_pk_bf16(g0[0], g0[1]); w.y = cvt_pk_bf16(g0[2], g0[3]); w.z = cvt_pk_bf16(g1[0], g1[1]); w.w = cvt_pk_bf16(g1[2], g1[3]); *(u32x4*)rp = w;
;                 w.x = cvt_pk_bf16(u0[0], u0[1]); w.y = cvt_pk_bf16(u0[2], u0[3]); w.z = cvt_pk_bf16(u1[0], u1[1]); w.w = cvt_pk_bf16(u1[2], u1[3]); *(u32x4*)(rp + DFF) = w; }
;         }
;         u32x2 ypk[2][4];
; #pragma unroll
;         for (int n = 0; n < 2; ++n) {
;             const int cn = c0 + 4 * n;
;             const f32x4 wg0 = *(const f32x4*)(cw + cn), wg1 = *(const f32x4*)(cw + UP_N + cn), wg2 = *(const f32x4*)(cw + 2 * UP_N + cn), bg = *(const f32x4*)(cb + cn);
;             const f32x4 wu0 = *(const f32x4*)(cw + DFF + cn), wu1 = *(const f32x4*)(cw + UP_N + DFF + cn), wu2 = *(const f32x4*)(cw + 2 * UP_N + DFF + cn), bu = *(const f32x4*)(cb + DFF + cn);
.LBB0_839:
	v_lshl_add_u32 v252, s1, 10, v192
	v_mad_u32_u24 v252, v134, 12, v252
	ds_read_b128 v[228:231], v252
	ds_read_b128 v[232:235], v252 offset:512
	v_lshl_or_b32 v213, s0, 7, v193
	v_lshlrev_b32_e32 v253, 2, v213
	global_load_dwordx4 v[144:147], v253, s[34:35]
	global_load_dwordx4 v[152:155], v253, s[40:41]
	global_load_dwordx4 v[160:163], v253, s[42:43]
	global_load_dwordx4 v[168:171], v253, s[36:37]
	global_load_dwordx4 v[180:183], v253, s[44:45]
	global_load_dwordx4 v[188:191], v253, s[46:47]
	global_load_dwordx4 v[200:203], v253, s[48:49]
	global_load_dwordx4 v[220:223], v253, s[50:51]
	global_load_dwordx4 v[148:151], v253, s[34:35] offset:16
	global_load_dwordx4 v[156:159], v253, s[40:41] offset:16
	global_load_dwordx4 v[164:167], v253, s[42:43] offset:16
	global_load_dwordx4 v[172:175], v253, s[36:37] offset:16
	global_load_dwordx4 v[184:187], v253, s[44:45] offset:16
	global_load_dwordx4 v[196:199], v253, s[46:47] offset:16
	global_load_dwordx4 v[204:207], v253, s[48:49] offset:16
	global_load_dwordx4 v[224:227], v253, s[50:51] offset:16
	s_waitcnt lgkmcnt(0)
	v_pk_mul_f32 v[124:125], v[124:125], v[228:229] op_sel_hi:[1,0]
	v_pk_mul_f32 v[126:127], v[126:127], v[228:229] op_sel_hi:[1,0]
	v_pk_mul_f32 v[120:121], v[120:121], v[228:229] op_sel_hi:[1,0]
	v_pk_mul_f32 v[122:123], v[122:123], v[228:229] op_sel_hi:[1,0]
	v_pk_mul_f32 v[116:117], v[116:117], v[228:229] op_sel_hi:[1,0]
	v_pk_mul_f32 v[118:119], v[118:119], v[228:229] op_sel_hi:[1,0]
	v_pk_mul_f32 v[112:113], v[112:113], v[228:229] op_sel_hi:[1,0]
	v_pk_mul_f32 v[114:115], v[114:115], v[228:229] op_sel_hi:[1,0]
	v_pk_mul_f32 v[68:69], v[68:69], v[228:229] op_sel:[0,1] op_sel_hi:[1,1]
	v_pk_mul_f32 v[70:71], v[70:71], v[228:229] op_sel:[0,1] op_sel_hi:[1,1]
	v_pk_mul_f32 v[64:65], v[64:65], v[228:229] op_sel:[0,1] op_sel_hi:[1,1]
	v_pk_mul_f32 v[66:67], v[66:67], v[228:229] op_sel:[0,1] op_sel_hi:[1,1]
	v_pk_mul_f32 v[52:53], v[52:53], v[228:229] op_sel:[0,1] op_sel_hi:[1,1]
	v_pk_mul_f32 v[54:55], v[54:55], v[228:229] op_sel:[0,1] op_sel_hi:[1,1]
	v_pk_mul_f32 v[48:49], v[48:49], v[228:229] op_sel:[0,1] op_sel_hi:[1,1]
	v_pk_mul_f32 v[50:51], v[50:51], v[228:229] op_sel:[0,1] op_sel_hi:[1,1]
	v_pk_mul_f32 v[60:61], v[60:61], v[230:231] op_sel_hi:[1,0]
	v_pk_mul_f32 v[62:63], v[62:63], v[230:231] op_sel_hi:[1,0]
	v_pk_mul_f32 v[20:21], v[20:21], v[230:231] op_sel_hi:[1,0]
	v_pk_mul_f32 v[22:23], v[22:23], v[230:231] op_sel_hi:[1,0]
	v_pk_mul_f32 v[44:45], v[44:45], v[230:231] op_sel_hi:[1,0]
	v_pk_mul_f32 v[46:47], v[46:47], v[230:231] op_sel_hi:[1,0]
	v_pk_mul_f32 v[16:17], v[16:17], v[230:231] op_sel_hi:[1,0]
	v_pk_mul_f32 v[18:19], v[18:19], v[230:231] op_sel_hi:[1,0]
	v_pk_mul_f32 v[108:109], v[108:109], v[230:231] op_sel:[0,1] op_sel_hi:[1,1]
	v_pk_mul_f32 v[110:111], v[110:111], v[230:231] op_sel:[0,1] op_sel_hi:[1,1]
	v_pk_mul_f32 v[104:105], v[104:105], v[230:231] op_sel:[0,1] op_sel_hi:[1,1]
	v_pk_mul_f32 v[106:107], v[106:107], v[230:231] op_sel:[0,1] op_sel_hi:[1,1]
	v_pk_mul_f32 v[100:101], v[100:101], v[230:231] op_sel:[0,1] op_sel_hi:[1,1]
	v_pk_mul_f32 v[102:103], v[102:103], v[230:231] op_sel:[0,1] op_sel_hi:[1,1]
	v_pk_mul_f32 v[96:97], v[96:97], v[230:231] op_sel:[0,1] op_sel_hi:[1,1]
	v_pk_mul_f32 v[98:99], v[98:99], v[230:231] op_sel:[0,1] op_sel_hi:[1,1]
	v_pk_mul_f32 v[92:93], v[92:93], v[232:233] op_sel_hi:[1,0]
	v_pk_mul_f32 v[94:95], v[94:95], v[232:233] op_sel_hi:[1,0]
	v_pk_mul_f32 v[88:89], v[88:89], v[232:233] op_sel_hi:[1,0]
	v_pk_mul_f32 v[90:91], v[90:91], v[232:233] op_sel_hi:[1,0]
	v_pk_mul_f32 v[84:85], v[84:85], v[232:233] op_sel_hi:[1,0]
	v_pk_mul_f32 v[86:87], v[86:87], v[232:233] op_sel_hi:[1,0]
	v_pk_mul_f32 v[80:81], v[80:81], v[232:233] op_sel_hi:[1,0]
	v_pk_mul_f32 v[82:83], v[82:83], v[232:233] op_sel_hi:[1,0]
	v_pk_mul_f32 v[36:37], v[36:37], v[232:233] op_sel:[0,1] op_sel_hi:[1,1]
	v_pk_mul_f32 v[38:39], v[38:39], v[232:233] op_sel:[0,1] op_sel_hi:[1,1]
	v_pk_mul_f32 v[12:13], v[12:13], v[232:233] op_sel:[0,1] op_sel_hi:[1,1]
	v_pk_mul_f32 v[14:15], v[14:15], v[232:233] op_sel:[0,1] op_sel_hi:[1,1]
	v_pk_mul_f32 v[28:29], v[28:29], v[232:233] op_sel:[0,1] op_sel_hi:[1,1]
	v_pk_mul_f32 v[30:31], v[30:31], v[232:233] op_sel:[0,1] op_sel_hi:[1,1]
	v_pk_mul_f32 v[8:9], v[8:9], v[232:233] op_sel:[0,1] op_sel_hi:[1,1]
	v_pk_mul_f32 v[10:11], v[10:11], v[232:233] op_sel:[0,1] op_sel_hi:[1,1]
	v_pk_mul_f32 v[32:33], v[32:33], v[234:235] op_sel_hi:[1,0]
	v_pk_mul_f32 v[34:35], v[34:35], v[234:235] op_sel_hi:[1,0]
	v_pk_mul_f32 v[4:5], v[4:5], v[234:235] op_sel_hi:[1,0]
	v_pk_mul_f32 v[6:7], v[6:7], v[234:235] op_sel_hi:[1,0]
	v_pk_mul_f32 v[24:25], v[24:25], v[234:235] op_sel_hi:[1,0]
	v_pk_mul_f32 v[26:27], v[26:27], v[234:235] op_sel_hi:[1,0]
	v_pk_mul_f32 v[0:1], v[0:1], v[234:235] op_sel_hi:[1,0]
	v_pk_mul_f32 v[2:3], v[2:3], v[234:235] op_sel_hi:[1,0]
	v_pk_mul_f32 v[76:77], v[76:77], v[234:235] op_sel:[0,1] op_sel_hi:[1,1]
	v_pk_mul_f32 v[78:79], v[78:79], v[234:235] op_sel:[0,1] op_sel_hi:[1,1]
	v_pk_mul_f32 v[56:57], v[56:57], v[234:235] op_sel:[0,1] op_sel_hi:[1,1]
	v_pk_mul_f32 v[58:59], v[58:59], v[234:235] op_sel:[0,1] op_sel_hi:[1,1]
	v_pk_mul_f32 v[72:73], v[72:73], v[234:235] op_sel:[0,1] op_sel_hi:[1,1]
	v_pk_mul_f32 v[74:75], v[74:75], v[234:235] op_sel:[0,1] op_sel_hi:[1,1]
	v_pk_mul_f32 v[40:41], v[40:41], v[234:235] op_sel:[0,1] op_sel_hi:[1,1]
	v_pk_mul_f32 v[42:43], v[42:43], v[234:235] op_sel:[0,1] op_sel_hi:[1,1]
	v_lshlrev_b32_e32 v235, 1, v213
	s_lshl_b32 s0, s18, 8
	s_add_i32 s0, s0, s69
	v_lshl_add_u32 v234, v134, 2, s0
	v_mul_lo_u32 v234, v234, s89
	v_add_u32_e32 v234, v234, v235
; __device__ __forceinline__ unsigned cvt_pk_bf16(float lo, float hi) { unsigned r; asm volatile("v_cvt_pk_bf16_f32 %0, %1, %2" : "=v"(r) : "v"(lo), "v"(hi)); return r; }
;     __device__ __forceinline__ void operator()(f32x4 (&acc)[2][2][4][2], const Unit& u, int wr, int wc, int fr, int fq, const LAS float* rtab) const {
;     ...
;         for (int ai = 0; ai < 2; ++ai) {
;             const int blk = (u.pm * BM + ai * HALF + wr * 64) >> 6;
;             if (fr < 2) { bf16_t* rp = raw + ((size_t)blk * 4 + fr) * UP_N + c0;
;                 const f32x4 g0 = acc[ai][0][0][0], g1 = acc[ai][0][0][1], u0 = acc[ai][1][0][0], u1 = acc[ai][1][0][1];
;                 u32x4 w; w.x = cvt_pk_bf16(g0[0], g0[1]); w.y = cvt_pk_bf16(g0[2], g0[3]); w.z = cvt_pk_bf16(g1[0], g1[1]); w.w = cvt_pk_bf16(g1[2], g1[3]); *(u32x4*)rp = w;
;                 w.x = cvt_pk_bf16(u0[0], u0[1]); w.y = cvt_pk_bf16(u0[2], u0[3]); w.z = cvt_pk_bf16(u1[0], u1[1]); w.w = cvt_pk_bf16(u1[2], u1[3]); *(u32x4*)(rp + DFF) = w; }
;             if (fr >= 14) { bf16_t* rp = raw + ((size_t)blk * 4 + (fr - 12)) * UP_N + c0;
;                 const f32x4 g0 = acc[ai][0][3][0], g1 = acc[ai][0][3][1], u0 = acc[ai][1][3][0], u1 = acc[ai][1][3][1];
;                 u32x4 w; w.x = cvt_pk_bf16(g0[0], g0[1]); w.y = cvt_pk_bf16(g0[2], g0[3]); w.z = cvt_pk_bf16(g1[0], g1[1]); w.w = cvt_pk_bf16(g1[2], g1[3]); *(u32x4*)rp = w;
;                 w.x = cvt_pk_bf16(u0[0], u0[1]); w.y = cvt_pk_bf16(u0[2], u0[3]); w.z = cvt_pk_bf16(u1[0], u1[1]); w.w = cvt_pk_bf16(u1[2], u1[3]); *(u32x4*)(rp + DFF) = w; }
;         }
	v_cmp_eq_u32_e64 s[54:55], 0, v134
	v_cmp_eq_u32_e64 s[56:57], 15, v134
	s_lshl_b32 s0, s18, 4
	s_lshr_b32 s1, s69, 4
	s_add_i32 s0, s0, s1
	s_add_i32 s1, s0, 0
	s_mul_i32 s1, s1, s88
	s_add_u32 s58, s30, s1
	s_addc_u32 s59, s31, 0
	s_mov_b64 exec, s[54:55]
	v_cvt_pk_bf16_f32 v244, v124, v125
	v_cvt_pk_bf16_f32 v245, v126, v127
	v_cvt_pk_bf16_f32 v246, v120, v121
	v_cvt_pk_bf16_f32 v247, v122, v123
	v_cvt_pk_bf16_f32 v248, v116, v117
	v_cvt_pk_bf16_f32 v249, v118, v119
	v_cvt_pk_bf16_f32 v250, v112, v113
	v_cvt_pk_bf16_f32 v251, v114, v115
	global_store_dwordx4 v235, v[244:247], s[58:59]
	s_add_u32 s58, s58, 0x2c00
	s_addc_u32 s59, s59, 0
	global_store_dwordx4 v235, v[248:251], s[58:59]
	s_add_i32 s1, s0, 1
	s_mul_i32 s1, s1, s88
	s_add_u32 s58, s30, s1
	s_addc_u32 s59, s31, 0
	s_mov_b64 exec, s[54:55]
	v_cvt_pk_bf16_f32 v236, v68, v69
	v_cvt_pk_bf16_f32 v237, v70, v71
	v_cvt_pk_bf16_f32 v238, v64, v65
	v_cvt_pk_bf16_f32 v239, v66, v67
	v_cvt_pk_bf16_f32 v240, v52, v53
	v_cvt_pk_bf16_f32 v241, v54, v55
	v_cvt_pk_bf16_f32 v242, v48, v49
	v_cvt_pk_bf16_f32 v243, v50, v51
	global_store_dwordx4 v235, v[236:239], s[58:59]
	s_add_u32 s58, s58, 0x2c00
	s_addc_u32 s59, s59, 0
	global_store_dwordx4 v235, v[240:243], s[58:59]
	s_add_i32 s1, s0, 2
	s_mul_i32 s1, s1, s88
	s_add_u32 s58, s30, s1
	s_addc_u32 s59, s31, 0
	s_mov_b64 exec, s[56:57]
	v_cvt_pk_bf16_f32 v244, v60, v61
	v_cvt_pk_bf16_f32 v245, v62, v63
	v_cvt_pk_bf16_f32 v246, v20, v21
	v_cvt_pk_bf16_f32 v247, v22, v23
	v_cvt_pk_bf16_f32 v248, v44, v45
	v_cvt_pk_bf16_f32 v249, v46, v47
	v_cvt_pk_bf16_f32 v250, v16, v17
	v_cvt_pk_bf16_f32 v251, v18, v19
	global_store_dwordx4 v235, v[244:247], s[58:59]
	s_add_u32 s58, s58, 0x2c00
	s_addc_u32 s59, s59, 0
	global_store_dwordx4 v235, v[248:251], s[58:59]
	s_add_i32 s1, s0, 3
	s_mul_i32 s1, s1, s88
	s_add_u32 s58, s30, s1
	s_addc_u32 s59, s31, 0
	s_mov_b64 exec, s[56:57]
	v_cvt_pk_bf16_f32 v236, v108, v109
	v_cvt_pk_bf16_f32 v237, v110, v111
	v_cvt_pk_bf16_f32 v238, v104, v105
	v_cvt_pk_bf16_f32 v239, v106, v107
	v_cvt_pk_bf16_f32 v240, v100, v101
	v_cvt_pk_bf16_f32 v241, v102, v103
	v_cvt_pk_bf16_f32 v242, v96, v97
	v_cvt_pk_bf16_f32 v243, v98, v99
	global_store_dwordx4 v235, v[236:239], s[58:59]
	s_add_u32 s58, s58, 0x2c00
	s_addc_u32 s59, s59, 0
	global_store_dwordx4 v235, v[240:243], s[58:59]
	s_add_i32 s1, s0, 8
	s_mul_i32 s1, s1, s88
	s_add_u32 s58, s30, s1
	s_addc_u32 s59, s31, 0
	s_mov_b64 exec, s[54:55]
	v_cvt_pk_bf16_f32 v244, v92, v93
	v_cvt_pk_bf16_f32 v245, v94, v95
	v_cvt_pk_bf16_f32 v246, v88, v89
	v_cvt_pk_bf16_f32 v247, v90, v91
	v_cvt_pk_bf16_f32 v248, v84, v85
	v_cvt_pk_bf16_f32 v249, v86, v87
	v_cvt_pk_bf16_f32 v250, v80, v81
	v_cvt_pk_bf16_f32 v251, v82, v83
	global_store_dwordx4 v235, v[244:247], s[58:59]
	s_add_u32 s58, s58, 0x2c00
	s_addc_u32 s59, s59, 0
	global_store_dwordx4 v235, v[248:251], s[58:59]
	s_add_i32 s1, s0, 9
	s_mul_i32 s1, s1, s88
	s_add_u32 s58, s30, s1
	s_addc_u32 s59, s31, 0
	s_mov_b64 exec, s[54:55]
	v_cvt_pk_bf16_f32 v236, v36, v37
	v_cvt_pk_bf16_f32 v237, v38, v39
	v_cvt_pk_bf16_f32 v238, v12, v13
	v_cvt_pk_bf16_f32 v239, v14, v15
	v_cvt_pk_bf16_f32 v240, v28, v29
	v_cvt_pk_bf16_f32 v241, v30, v31
	v_cvt_pk_bf16_f32 v242, v8, v9
	v_cvt_pk_bf16_f32 v243, v10, v11
	global_store_dwordx4 v235, v[236:239], s[58:59]
	s_add_u32 s58, s58, 0x2c00
	s_addc_u32 s59, s59, 0
	global_store_dwordx4 v235, v[240:243], s[58:59]
	s_add_i32 s1, s0, 10
	s_mul_i32 s1, s1, s88
	s_add_u32 s58, s30, s1
	s_addc_u32 s59, s31, 0
	s_mov_b64 exec, s[56:57]
	v_cvt_pk_bf16_f32 v244, v32, v33
	v_cvt_pk_bf16_f32 v245, v34, v35
	v_cvt_pk_bf16_f32 v246, v4, v5
	v_cvt_pk_bf16_f32 v247, v6, v7
	v_cvt_pk_bf16_f32 v248, v24, v25
	v_cvt_pk_bf16_f32 v249, v26, v27
	v_cvt_pk_bf16_f32 v250, v0, v1
	v_cvt_pk_bf16_f32 v251, v2, v3
	global_store_dwordx4 v235, v[244:247], s[58:59]
	s_add_u32 s58, s58, 0x2c00
	s_addc_u32 s59, s59, 0
	global_store_dwordx4 v235, v[248:251], s[58:59]
	s_add_i32 s1, s0, 11
	s_mul_i32 s1, s1, s88
	s_add_u32 s58, s30, s1
	s_addc_u32 s59, s31, 0
	s_mov_b64 exec, s[56:57]
	v_cvt_pk_bf16_f32 v236, v76, v77
	v_cvt_pk_bf16_f32 v237, v78, v79
	v_cvt_pk_bf16_f32 v238, v56, v57
	v_cvt_pk_bf16_f32 v239, v58, v59
	v_cvt_pk_bf16_f32 v240, v72, v73
	v_cvt_pk_bf16_f32 v241, v74, v75
	v_cvt_pk_bf16_f32 v242, v40, v41
	v_cvt_pk_bf16_f32 v243, v42, v43
	global_store_dwordx4 v235, v[236:239], s[58:59]
	s_add_u32 s58, s58, 0x2c00
	s_addc_u32 s59, s59, 0
	global_store_dwordx4 v235, v[240:243], s[58:59]
	s_mov_b64 exec, -1
	s_waitcnt vmcnt(24)
; __device__ __forceinline__ unsigned cvt_pk_bf16(float lo, float hi) { unsigned r; asm volatile("v_cvt_pk_bf16_f32 %0, %1, %2" : "=v"(r) : "v"(lo), "v"(hi)); return r; }
; template <int CTRL> __device__ __forceinline__ float dppz(float v) { return __int_as_float(__builtin_amdgcn_update_dpp(0, __float_as_int(v), CTRL, 0xf, 0xf, true)); }
;     __device__ __forceinline__ void operator()(f32x4 (&acc)[2][2][4][2], const Unit& u, int wr, int wc, int fr, int fq, const LAS float* rtab) const {
;     ...
;                     for (int jj = 0; jj < 4; ++jj) {
;                         const float gc = acc[ai][0][m][n][jj], uc = acc[ai][1][m][n][jj];
;                         const float gb = m > 0 ? acc[ai][0][m - 1][n][jj] : 0.f, ga = m < 3 ? acc[ai][0][m + 1][n][jj] : 0.f;
;                         const float ub = m > 0 ? acc[ai][1][m - 1][n][jj] : 0.f, ua = m < 3 ? acc[ai][1][m + 1][n][jj] : 0.f;
;                         const float gp = dppz<0x111>(gc) + dppz<0x10F>(gb), gn = dppz<0x101>(gc) + dppz<0x11F>(ga);
;                         const float up = dppz<0x111>(uc) + dppz<0x10F>(ub), un = dppz<0x101>(uc) + dppz<0x11F>(ua);
;                         const float hg = wg0[jj] * gp + wg1[jj] * gc + wg2[jj] * gn + bg[jj];
;                         const float hu = wu0[jj] * up + wu1[jj] * uc + wu2[jj] * un + bu[jj];
;                         const float sg = __builtin_amdgcn_rcpf(1.f + __builtin_amdgcn_exp2f(-1.4426950408889634f * hg));
;                         y[jj] = hg * sg * hu; }
;                     u32x2 pk; pk.x = cvt_pk_bf16(y[0], y[1]); pk.y = cvt_pk_bf16(y[2], y[3]);
	s_mov_b32 s54, 0xbfb8aa3b
	s_mov_b32 s56, 1.0
	v_pk_fma_f32 v[142:143], v[152:153], v[124:125], v[168:169]
	v_pk_fma_f32 v[178:179], v[152:153], v[68:69], v[168:169]
	v_pk_fma_f32 v[210:211], v[152:153], v[60:61], v[168:169]
	v_pk_fma_f32 v[212:213], v[152:153], v[108:109], v[168:169]
	v_pk_fma_f32 v[142:143], v[160:161], v[68:69], v[142:143]
	v_pk_fma_f32 v[178:179], v[144:145], v[124:125], v[178:179]
	v_pk_fma_f32 v[210:211], v[144:145], v[68:69], v[210:211]
	v_pk_fma_f32 v[212:213], v[144:145], v[60:61], v[212:213]
	v_pk_fma_f32 v[178:179], v[160:161], v[60:61], v[178:179]
	v_pk_fma_f32 v[210:211], v[160:161], v[108:109], v[210:211]
	v_fmac_f32_dpp v142, v108, v144 row_shr:1 row_mask:0xf bank_mask:0xf bound_ctrl:1
	v_fmac_f32_dpp v212, v124, v160 row_shl:1 row_mask:0xf bank_mask:0xf bound_ctrl:1
	v_fmac_f32_dpp v143, v109, v145 row_shr:1 row_mask:0xf bank_mask:0xf bound_ctrl:1
	v_fmac_f32_dpp v213, v125, v161 row_shl:1 row_mask:0xf bank_mask:0xf bound_ctrl:1
	v_pk_mul_f32 v[218:219], v[142:143], s[54:55] op_sel_hi:[1,0]
	v_pk_mul_f32 v[252:253], v[178:179], s[54:55] op_sel_hi:[1,0]
	v_pk_mul_f32 v[228:229], v[210:211], s[54:55] op_sel_hi:[1,0]
	v_pk_mul_f32 v[230:231], v[212:213], s[54:55] op_sel_hi:[1,0]
	v_exp_f32_e32 v218, v218
	v_exp_f32_e32 v219, v219
	v_exp_f32_e32 v252, v252
	v_exp_f32_e32 v253, v253
	v_exp_f32_e32 v228, v228
	v_exp_f32_e32 v229, v229
	v_exp_f32_e32 v230, v230
	v_exp_f32_e32 v231, v231
	v_pk_add_f32 v[218:219], v[218:219], s[56:57] op_sel_hi:[1,0]
	v_pk_add_f32 v[252:253], v[252:253], s[56:57] op_sel_hi:[1,0]
	v_pk_add_f32 v[228:229], v[228:229], s[56:57] op_sel_hi:[1,0]
	v_pk_add_f32 v[230:231], v[230:231], s[56:57] op_sel_hi:[1,0]
	v_rcp_f32_e32 v218, v218
	v_rcp_f32_e32 v219, v219
	v_rcp_f32_e32 v252, v252
	v_rcp_f32_e32 v253, v253
	v_rcp_f32_e32 v228, v228
	v_rcp_f32_e32 v229, v229
	v_rcp_f32_e32 v230, v230
	v_rcp_f32_e32 v231, v231
	v_pk_mul_f32 v[142:143], v[142:143], v[218:219]
	v_pk_mul_f32 v[178:179], v[178:179], v[252:253]
	v_pk_mul_f32 v[210:211], v[210:211], v[228:229]
	v_pk_mul_f32 v[212:213], v[212:213], v[230:231]
	v_pk_fma_f32 v[218:219], v[188:189], v[116:117], v[220:221]
	v_pk_fma_f32 v[252:253], v[188:189], v[52:53], v[220:221]
	v_pk_fma_f32 v[228:229], v[188:189], v[44:45], v[220:221]
	v_pk_fma_f32 v[230:231], v[188:189], v[100:101], v[220:221]
	v_pk_fma_f32 v[218:219], v[200:201], v[52:53], v[218:219]
	v_pk_fma_f32 v[252:253], v[180:181], v[116:117], v[252:253]
	v_pk_fma_f32 v[228:229], v[180:181], v[52:53], v[228:229]
	v_pk_fma_f32 v[230:231], v[180:181], v[44:45], v[230:231]
	v_pk_fma_f32 v[252:253], v[200:201], v[44:45], v[252:253]
	v_pk_fma_f32 v[228:229], v[200:201], v[100:101], v[228:229]
	v_fmac_f32_dpp v218, v100, v180 row_shr:1 row_mask:0xf bank_mask:0xf bound_ctrl:1
	v_fmac_f32_dpp v230, v116, v200 row_shl:1 row_mask:0xf bank_mask:0xf bound_ctrl:1
	v_fmac_f32_dpp v219, v101, v181 row_shr:1 row_mask:0xf bank_mask:0xf bound_ctrl:1
	v_fmac_f32_dpp v231, v117, v201 row_shl:1 row_mask:0xf bank_mask:0xf bound_ctrl:1
	v_pk_mul_f32 v[142:143], v[142:143], v[218:219]
	v_pk_mul_f32 v[178:179], v[178:179], v[252:253]
	v_pk_mul_f32 v[210:211], v[210:211], v[228:229]
	v_pk_mul_f32 v[212:213], v[212:213], v[230:231]
	v_cvt_pk_bf16_f32 v236, v142, v143
	v_cvt_pk_bf16_f32 v240, v178, v179
	v_cvt_pk_bf16_f32 v244, v210, v211
	v_cvt_pk_bf16_f32 v248, v212, v213
	v_pk_fma_f32 v[142:143], v[154:155], v[126:127], v[170:171]
	v_pk_fma_f32 v[178:179], v[154:155], v[70:71], v[170:171]
	v_pk_fma_f32 v[210:211], v[154:155], v[62:63], v[170:171]
	v_pk_fma_f32 v[212:213], v[154:155], v[110:111], v[170:171]
	v_pk_fma_f32 v[142:143], v[162:163], v[70:71], v[142:143]
	v_pk_fma_f32 v[178:179], v[146:147], v[126:127], v[178:179]
	v_pk_fma_f32 v[210:211], v[146:147], v[70:71], v[210:211]
	v_pk_fma_f32 v[212:213], v[146:147], v[62:63], v[212:213]
	v_pk_fma_f32 v[178:179], v[162:163], v[62:63], v[178:179]
	v_pk_fma_f32 v[210:211], v[162:163], v[110:111], v[210:211]
	v_fmac_f32_dpp v142, v110, v146 row_shr:1 row_mask:0xf bank_mask:0xf bound_ctrl:1
	v_fmac_f32_dpp v212, v126, v162 row_shl:1 row_mask:0xf bank_mask:0xf bound_ctrl:1
	v_fmac_f32_dpp v143, v111, v147 row_shr:1 row_mask:0xf bank_mask:0xf bound_ctrl:1
	v_fmac_f32_dpp v213, v127, v163 row_shl:1 row_mask:0xf bank_mask:0xf bound_ctrl:1
	v_pk_mul_f32 v[218:219], v[142:143], s[54:55] op_sel_hi:[1,0]
	v_pk_mul_f32 v[252:253], v[178:179], s[54:55] op_sel_hi:[1,0]
	v_pk_mul_f32 v[228:229], v[210:211], s[54:55] op_sel_hi:[1,0]
	v_pk_mul_f32 v[230:231], v[212:213], s[54:55] op_sel_hi:[1,0]
	v_exp_f32_e32 v218, v218
	v_exp_f32_e32 v219, v219
	v_exp_f32_e32 v252, v252
	v_exp_f32_e32 v253, v253
	v_exp_f32_e32 v228, v228
	v_exp_f32_e32 v229, v229
	v_exp_f32_e32 v230, v230
	v_exp_f32_e32 v231, v231
	v_pk_add_f32 v[218:219], v[218:219], s[56:57] op_sel_hi:[1,0]
	v_pk_add_f32 v[252:253], v[252:253], s[56:57] op_sel_hi:[1,0]
	v_pk_add_f32 v[228:229], v[228:229], s[56:57] op_sel_hi:[1,0]
	v_pk_add_f32 v[230:231], v[230:231], s[56:57] op_sel_hi:[1,0]
	v_rcp_f32_e32 v218, v218
	v_rcp_f32_e32 v219, v219
	v_rcp_f32_e32 v252, v252
	v_rcp_f32_e32 v253, v253
	v_rcp_f32_e32 v228, v228
	v_rcp_f32_e32 v229, v229
	v_rcp_f32_e32 v230, v230
	v_rcp_f32_e32 v231, v231
	v_pk_mul_f32 v[142:143], v[142:143], v[218:219]
	v_pk_mul_f32 v[178:179], v[178:179], v[252:253]
	v_pk_mul_f32 v[210:211], v[210:211], v[228:229]
	v_pk_mul_f32 v[212:213], v[212:213], v[230:231]
	v_pk_fma_f32 v[218:219], v[190:191], v[118:119], v[222:223]
	v_pk_fma_f32 v[252:253], v[190:191], v[54:55], v[222:223]
	v_pk_fma_f32 v[228:229], v[190:191], v[46:47], v[222:223]
	v_pk_fma_f32 v[230:231], v[190:191], v[102:103], v[222:223]
	v_pk_fma_f32 v[218:219], v[202:203], v[54:55], v[218:219]
	v_pk_fma_f32 v[252:253], v[182:183], v[118:119], v[252:253]
	v_pk_fma_f32 v[228:229], v[182:183], v[54:55], v[228:229]
	v_pk_fma_f32 v[230:231], v[182:183], v[46:47], v[230:231]
	v_pk_fma_f32 v[252:253], v[202:203], v[46:47], v[252:253]
	v_pk_fma_f32 v[228:229], v[202:203], v[102:103], v[228:229]
	v_fmac_f32_dpp v218, v102, v182 row_shr:1 row_mask:0xf bank_mask:0xf bound_ctrl:1
	v_fmac_f32_dpp v230, v118, v202 row_shl:1 row_mask:0xf bank_mask:0xf bound_ctrl:1
	v_fmac_f32_dpp v219, v103, v183 row_shr:1 row_mask:0xf bank_mask:0xf bound_ctrl:1
	v_fmac_f32_dpp v231, v119, v203 row_shl:1 row_mask:0xf bank_mask:0xf bound_ctrl:1
	v_pk_mul_f32 v[142:143], v[142:143], v[218:219]
	v_pk_mul_f32 v[178:179], v[178:179], v[252:253]
	v_pk_mul_f32 v[210:211], v[210:211], v[228:229]
	v_pk_mul_f32 v[212:213], v[212:213], v[230:231]
	v_cvt_pk_bf16_f32 v237, v142, v143
	v_cvt_pk_bf16_f32 v241, v178, v179
	v_cvt_pk_bf16_f32 v245, v210, v211
	v_cvt_pk_bf16_f32 v249, v212, v213
	s_waitcnt vmcnt(16)
; __device__ __forceinline__ unsigned cvt_pk_bf16(float lo, float hi) { unsigned r; asm volatile("v_cvt_pk_bf16_f32 %0, %1, %2" : "=v"(r) : "v"(lo), "v"(hi)); return r; }
; template <int CTRL> __device__ __forceinline__ float dppz(float v) { return __int_as_float(__builtin_amdgcn_update_dpp(0, __float_as_int(v), CTRL, 0xf, 0xf, true)); }
;     __device__ __forceinline__ void operator()(f32x4 (&acc)[2][2][4][2], const Unit& u, int wr, int wc, int fr, int fq, const LAS float* rtab) const {
;     ...
;                     for (int jj = 0; jj < 4; ++jj) {
;                         const float gc = acc[ai][0][m][n][jj], uc = acc[ai][1][m][n][jj];
;                         const float gb = m > 0 ? acc[ai][0][m - 1][n][jj] : 0.f, ga = m < 3 ? acc[ai][0][m + 1][n][jj] : 0.f;
;                         const float ub = m > 0 ? acc[ai][1][m - 1][n][jj] : 0.f, ua = m < 3 ? acc[ai][1][m + 1][n][jj] : 0.f;
;                         const float gp = dppz<0x111>(gc) + dppz<0x10F>(gb), gn = dppz<0x101>(gc) + dppz<0x11F>(ga);
;                         const float up = dppz<0x111>(uc) + dppz<0x10F>(ub), un = dppz<0x101>(uc) + dppz<0x11F>(ua);
;                         const float hg = wg0[jj] * gp + wg1[jj] * gc + wg2[jj] * gn + bg[jj];
;                         const float hu = wu0[jj] * up + wu1[jj] * uc + wu2[jj] * un + bu[jj];
;                         const float sg = __builtin_amdgcn_rcpf(1.f + __builtin_amdgcn_exp2f(-1.4426950408889634f * hg));
;                         y[jj] = hg * sg * hu; }
;                     u32x2 pk; pk.x = cvt_pk_bf16(y[0], y[1]); pk.y = cvt_pk_bf16(y[2], y[3]);
	v_pk_fma_f32 v[142:143], v[156:157], v[120:121], v[172:173]
	v_pk_fma_f32 v[178:179], v[156:157], v[64:65], v[172:173]
	v_pk_fma_f32 v[210:211], v[156:157], v[20:21], v[172:173]
	v_pk_fma_f32 v[212:213], v[156:157], v[104:105], v[172:173]
	v_pk_fma_f32 v[142:143], v[164:165], v[64:65], v[142:143]
	v_pk_fma_f32 v[178:179], v[148:149], v[120:121], v[178:179]
	v_pk_fma_f32 v[210:211], v[148:149], v[64:65], v[210:211]
	v_pk_fma_f32 v[212:213], v[148:149], v[20:21], v[212:213]
	v_pk_fma_f32 v[178:179], v[164:165], v[20:21], v[178:179]
	v_pk_fma_f32 v[210:211], v[164:165], v[104:105], v[210:211]
	v_fmac_f32_dpp v142, v104, v148 row_shr:1 row_mask:0xf bank_mask:0xf bound_ctrl:1
	v_fmac_f32_dpp v212, v120, v164 row_shl:1 row_mask:0xf bank_mask:0xf bound_ctrl:1
	v_fmac_f32_dpp v143, v105, v149 row_shr:1 row_mask:0xf bank_mask:0xf bound_ctrl:1
	v_fmac_f32_dpp v213, v121, v165 row_shl:1 row_mask:0xf bank_mask:0xf bound_ctrl:1
	v_pk_mul_f32 v[218:219], v[142:143], s[54:55] op_sel_hi:[1,0]
	v_pk_mul_f32 v[252:253], v[178:179], s[54:55] op_sel_hi:[1,0]
	v_pk_mul_f32 v[228:229], v[210:211], s[54:55] op_sel_hi:[1,0]
	v_pk_mul_f32 v[230:231], v[212:213], s[54:55] op_sel_hi:[1,0]
	v_exp_f32_e32 v218, v218
	v_exp_f32_e32 v219, v219
	v_exp_f32_e32 v252, v252
	v_exp_f32_e32 v253, v253
	v_exp_f32_e32 v228, v228
	v_exp_f32_e32 v229, v229
	v_exp_f32_e32 v230, v230
	v_exp_f32_e32 v231, v231
	v_pk_add_f32 v[218:219], v[218:219], s[56:57] op_sel_hi:[1,0]
	v_pk_add_f32 v[252:253], v[252:253], s[56:57] op_sel_hi:[1,0]
	v_pk_add_f32 v[228:229], v[228:229], s[56:57] op_sel_hi:[1,0]
	v_pk_add_f32 v[230:231], v[230:231], s[56:57] op_sel_hi:[1,0]
	v_rcp_f32_e32 v218, v218
	v_rcp_f32_e32 v219, v219
	v_rcp_f32_e32 v252, v252
	v_rcp_f32_e32 v253, v253
	v_rcp_f32_e32 v228, v228
	v_rcp_f32_e32 v229, v229
	v_rcp_f32_e32 v230, v230
	v_rcp_f32_e32 v231, v231
	v_pk_mul_f32 v[142:143], v[142:143], v[218:219]
	v_pk_mul_f32 v[178:179], v[178:179], v[252:253]
	v_pk_mul_f32 v[210:211], v[210:211], v[228:229]
	v_pk_mul_f32 v[212:213], v[212:213], v[230:231]
	v_pk_fma_f32 v[218:219], v[196:197], v[112:113], v[224:225]
	v_pk_fma_f32 v[252:253], v[196:197], v[48:49], v[224:225]
	v_pk_fma_f32 v[228:229], v[196:197], v[16:17], v[224:225]
	v_pk_fma_f32 v[230:231], v[196:197], v[96:97], v[224:225]
	v_pk_fma_f32 v[218:219], v[204:205], v[48:49], v[218:219]
	v_pk_fma_f32 v[252:253], v[184:185], v[112:113], v[252:253]
	v_pk_fma_f32 v[228:229], v[184:185], v[48:49], v[228:229]
	v_pk_fma_f32 v[230:231], v[184:185], v[16:17], v[230:231]
	v_pk_fma_f32 v[252:253], v[204:205], v[16:17], v[252:253]
	v_pk_fma_f32 v[228:229], v[204:205], v[96:97], v[228:229]
	v_fmac_f32_dpp v218, v96, v184 row_shr:1 row_mask:0xf bank_mask:0xf bound_ctrl:1
	v_fmac_f32_dpp v230, v112, v204 row_shl:1 row_mask:0xf bank_mask:0xf bound_ctrl:1
	v_fmac_f32_dpp v219, v97, v185 row_shr:1 row_mask:0xf bank_mask:0xf bound_ctrl:1
	v_fmac_f32_dpp v231, v113, v205 row_shl:1 row_mask:0xf bank_mask:0xf bound_ctrl:1
	v_pk_mul_f32 v[142:143], v[142:143], v[218:219]
	v_pk_mul_f32 v[178:179], v[178:179], v[252:253]
	v_pk_mul_f32 v[210:211], v[210:211], v[228:229]
	v_pk_mul_f32 v[212:213], v[212:213], v[230:231]
	v_cvt_pk_bf16_f32 v238, v142, v143
	v_cvt_pk_bf16_f32 v242, v178, v179
	v_cvt_pk_bf16_f32 v246, v210, v211
	v_cvt_pk_bf16_f32 v250, v212, v213
	v_pk_fma_f32 v[142:143], v[158:159], v[122:123], v[174:175]
	v_pk_fma_f32 v[178:179], v[158:159], v[66:67], v[174:175]
	v_pk_fma_f32 v[210:211], v[158:159], v[22:23], v[174:175]
	v_pk_fma_f32 v[212:213], v[158:159], v[106:107], v[174:175]
	v_pk_fma_f32 v[142:143], v[166:167], v[66:67], v[142:143]
	v_pk_fma_f32 v[178:179], v[150:151], v[122:123], v[178:179]
	v_pk_fma_f32 v[210:211], v[150:151], v[66:67], v[210:211]
	v_pk_fma_f32 v[212:213], v[150:151], v[22:23], v[212:213]
	v_pk_fma_f32 v[178:179], v[166:167], v[22:23], v[178:179]
	v_pk_fma_f32 v[210:211], v[166:167], v[106:107], v[210:211]
	v_fmac_f32_dpp v142, v106, v150 row_shr:1 row_mask:0xf bank_mask:0xf bound_ctrl:1
	v_fmac_f32_dpp v212, v122, v166 row_shl:1 row_mask:0xf bank_mask:0xf bound_ctrl:1
	v_fmac_f32_dpp v143, v107, v151 row_shr:1 row_mask:0xf bank_mask:0xf bound_ctrl:1
	v_fmac_f32_dpp v213, v123, v167 row_shl:1 row_mask:0xf bank_mask:0xf bound_ctrl:1
	v_pk_mul_f32 v[218:219], v[142:143], s[54:55] op_sel_hi:[1,0]
	v_pk_mul_f32 v[252:253], v[178:179], s[54:55] op_sel_hi:[1,0]
	v_pk_mul_f32 v[228:229], v[210:211], s[54:55] op_sel_hi:[1,0]
	v_pk_mul_f32 v[230:231], v[212:213], s[54:55] op_sel_hi:[1,0]
	v_exp_f32_e32 v218, v218
	v_exp_f32_e32 v219, v219
	v_exp_f32_e32 v252, v252
	v_exp_f32_e32 v253, v253
	v_exp_f32_e32 v228, v228
	v_exp_f32_e32 v229, v229
	v_exp_f32_e32 v230, v230
	v_exp_f32_e32 v231, v231
	v_pk_add_f32 v[218:219], v[218:219], s[56:57] op_sel_hi:[1,0]
	v_pk_add_f32 v[252:253], v[252:253], s[56:57] op_sel_hi:[1,0]
	v_pk_add_f32 v[228:229], v[228:229], s[56:57] op_sel_hi:[1,0]
	v_pk_add_f32 v[230:231], v[230:231], s[56:57] op_sel_hi:[1,0]
	v_rcp_f32_e32 v218, v218
	v_rcp_f32_e32 v219, v219
	v_rcp_f32_e32 v252, v252
	v_rcp_f32_e32 v253, v253
	v_rcp_f32_e32 v228, v228
	v_rcp_f32_e32 v229, v229
	v_rcp_f32_e32 v230, v230
	v_rcp_f32_e32 v231, v231
	v_pk_mul_f32 v[142:143], v[142:143], v[218:219]
	v_pk_mul_f32 v[178:179], v[178:179], v[252:253]
	v_pk_mul_f32 v[210:211], v[210:211], v[228:229]
	v_pk_mul_f32 v[212:213], v[212:213], v[230:231]
	v_pk_fma_f32 v[218:219], v[198:199], v[114:115], v[226:227]
	v_pk_fma_f32 v[252:253], v[198:199], v[50:51], v[226:227]
	v_pk_fma_f32 v[228:229], v[198:199], v[18:19], v[226:227]
	v_pk_fma_f32 v[230:231], v[198:199], v[98:99], v[226:227]
	v_pk_fma_f32 v[218:219], v[206:207], v[50:51], v[218:219]
; __device__ __forceinline__ unsigned cvt_pk_bf16(float lo, float hi) { unsigned r; asm volatile("v_cvt_pk_bf16_f32 %0, %1, %2" : "=v"(r) : "v"(lo), "v"(hi)); return r; }
; template <int CTRL> __device__ __forceinline__ float dppz(float v) { return __int_as_float(__builtin_amdgcn_update_dpp(0, __float_as_int(v), CTRL, 0xf, 0xf, true)); }
;     __device__ __forceinline__ void operator()(f32x4 (&acc)[2][2][4][2], const Unit& u, int wr, int wc, int fr, int fq, const LAS float* rtab) const {
;     ...
;                     for (int jj = 0; jj < 4; ++jj) {
;                         const float gc = acc[ai][0][m][n][jj], uc = acc[ai][1][m][n][jj];
;                         const float gb = m > 0 ? acc[ai][0][m - 1][n][jj] : 0.f, ga = m < 3 ? acc[ai][0][m + 1][n][jj] : 0.f;
;                         const float ub = m > 0 ? acc[ai][1][m - 1][n][jj] : 0.f, ua = m < 3 ? acc[ai][1][m + 1][n][jj] : 0.f;
;                         const float gp = dppz<0x111>(gc) + dppz<0x10F>(gb), gn = dppz<0x101>(gc) + dppz<0x11F>(ga);
;                         const float up = dppz<0x111>(uc) + dppz<0x10F>(ub), un = dppz<0x101>(uc) + dppz<0x11F>(ua);
;                         const float hg = wg0[jj] * gp + wg1[jj] * gc + wg2[jj] * gn + bg[jj];
;                         const float hu = wu0[jj] * up + wu1[jj] * uc + wu2[jj] * un + bu[jj];
;                         const float sg = __builtin_amdgcn_rcpf(1.f + __builtin_amdgcn_exp2f(-1.4426950408889634f * hg));
;                         y[jj] = hg * sg * hu; }
;                     u32x2 pk; pk.x = cvt_pk_bf16(y[0], y[1]); pk.y = cvt_pk_bf16(y[2], y[3]);
;                     if (n == 0) ypk[ai][m] = pk;
;                     else {
;                         const bool deferred = (m == 0 && fr == 0) || (m == 3 && fr == 15);
;                         if (!deferred) { u32x4 w; w.x = ypk[ai][m].x; w.y = ypk[ai][m].y; w.z = pk.x; w.w = pk.y; *(u32x4*)(act + (size_t)(r64 + m * 16 + fr) * DFF + c0) = w; } }
	v_pk_fma_f32 v[252:253], v[186:187], v[114:115], v[252:253]
	v_pk_fma_f32 v[228:229], v[186:187], v[50:51], v[228:229]
	v_pk_fma_f32 v[230:231], v[186:187], v[18:19], v[230:231]
	v_pk_fma_f32 v[252:253], v[206:207], v[18:19], v[252:253]
	v_pk_fma_f32 v[228:229], v[206:207], v[98:99], v[228:229]
	v_fmac_f32_dpp v218, v98, v186 row_shr:1 row_mask:0xf bank_mask:0xf bound_ctrl:1
	v_fmac_f32_dpp v230, v114, v206 row_shl:1 row_mask:0xf bank_mask:0xf bound_ctrl:1
	v_fmac_f32_dpp v219, v99, v187 row_shr:1 row_mask:0xf bank_mask:0xf bound_ctrl:1
	v_fmac_f32_dpp v231, v115, v207 row_shl:1 row_mask:0xf bank_mask:0xf bound_ctrl:1
	v_pk_mul_f32 v[142:143], v[142:143], v[218:219]
	v_pk_mul_f32 v[178:179], v[178:179], v[252:253]
	v_pk_mul_f32 v[210:211], v[210:211], v[228:229]
	v_pk_mul_f32 v[212:213], v[212:213], v[230:231]
	v_cvt_pk_bf16_f32 v239, v142, v143
	v_cvt_pk_bf16_f32 v243, v178, v179
	v_cvt_pk_bf16_f32 v247, v210, v211
	v_cvt_pk_bf16_f32 v251, v212, v213
	s_mov_b64 s[58:59], s[28:29]
	s_mov_b64 exec, s[12:13]
	global_store_dwordx4 v234, v[236:239], s[58:59]
	s_mov_b64 exec, -1
	s_add_u32 s58, s28, 0x2c00
	s_addc_u32 s59, s29, 0
	global_store_dwordx4 v234, v[240:243], s[58:59]
	s_add_u32 s58, s28, 0x5800
	s_addc_u32 s59, s29, 0
	global_store_dwordx4 v234, v[244:247], s[58:59]
	s_add_u32 s58, s28, 0x8400
	s_addc_u32 s59, s29, 0
	s_mov_b64 exec, s[10:11]
	global_store_dwordx4 v234, v[248:251], s[58:59]
	s_mov_b64 exec, -1
	v_pk_fma_f32 v[142:143], v[152:153], v[92:93], v[168:169]
	v_pk_fma_f32 v[178:179], v[152:153], v[36:37], v[168:169]
	v_pk_fma_f32 v[210:211], v[152:153], v[32:33], v[168:169]
	v_pk_fma_f32 v[212:213], v[152:153], v[76:77], v[168:169]
	v_pk_fma_f32 v[142:143], v[160:161], v[36:37], v[142:143]
	v_pk_fma_f32 v[178:179], v[144:145], v[92:93], v[178:179]
	v_pk_fma_f32 v[210:211], v[144:145], v[36:37], v[210:211]
	v_pk_fma_f32 v[212:213], v[144:145], v[32:33], v[212:213]
	v_pk_fma_f32 v[178:179], v[160:161], v[32:33], v[178:179]
	v_pk_fma_f32 v[210:211], v[160:161], v[76:77], v[210:211]
	v_fmac_f32_dpp v142, v76, v144 row_shr:1 row_mask:0xf bank_mask:0xf bound_ctrl:1
	v_fmac_f32_dpp v212, v92, v160 row_shl:1 row_mask:0xf bank_mask:0xf bound_ctrl:1
	v_fmac_f32_dpp v143, v77, v145 row_shr:1 row_mask:0xf bank_mask:0xf bound_ctrl:1
	v_fmac_f32_dpp v213, v93, v161 row_shl:1 row_mask:0xf bank_mask:0xf bound_ctrl:1
	v_pk_mul_f32 v[218:219], v[142:143], s[54:55] op_sel_hi:[1,0]
	v_pk_mul_f32 v[252:253], v[178:179], s[54:55] op_sel_hi:[1,0]
	v_pk_mul_f32 v[228:229], v[210:211], s[54:55] op_sel_hi:[1,0]
	v_pk_mul_f32 v[230:231], v[212:213], s[54:55] op_sel_hi:[1,0]
	v_exp_f32_e32 v218, v218
	v_exp_f32_e32 v219, v219
	v_exp_f32_e32 v252, v252
	v_exp_f32_e32 v253, v253
	v_exp_f32_e32 v228, v228
	v_exp_f32_e32 v229, v229
	v_exp_f32_e32 v230, v230
	v_exp_f32_e32 v231, v231
	v_pk_add_f32 v[218:219], v[218:219], s[56:57] op_sel_hi:[1,0]
	v_pk_add_f32 v[252:253], v[252:253], s[56:57] op_sel_hi:[1,0]
	v_pk_add_f32 v[228:229], v[228:229], s[56:57] op_sel_hi:[1,0]
	v_pk_add_f32 v[230:231], v[230:231], s[56:57] op_sel_hi:[1,0]
	v_rcp_f32_e32 v218, v218
	v_rcp_f32_e32 v219, v219
	v_rcp_f32_e32 v252, v252
	v_rcp_f32_e32 v253, v253
	v_rcp_f32_e32 v228, v228
	v_rcp_f32_e32 v229, v229
	v_rcp_f32_e32 v230, v230
	v_rcp_f32_e32 v231, v231
	v_pk_mul_f32 v[142:143], v[142:143], v[218:219]
	v_pk_mul_f32 v[178:179], v[178:179], v[252:253]
	v_pk_mul_f32 v[210:211], v[210:211], v[228:229]
	v_pk_mul_f32 v[212:213], v[212:213], v[230:231]
	v_pk_fma_f32 v[218:219], v[188:189], v[84:85], v[220:221]
	v_pk_fma_f32 v[252:253], v[188:189], v[28:29], v[220:221]
	v_pk_fma_f32 v[228:229], v[188:189], v[24:25], v[220:221]
	v_pk_fma_f32 v[230:231], v[188:189], v[72:73], v[220:221]
	v_pk_fma_f32 v[218:219], v[200:201], v[28:29], v[218:219]
	v_pk_fma_f32 v[252:253], v[180:181], v[84:85], v[252:253]
	v_pk_fma_f32 v[228:229], v[180:181], v[28:29], v[228:229]
	v_pk_fma_f32 v[230:231], v[180:181], v[24:25], v[230:231]
	v_pk_fma_f32 v[252:253], v[200:201], v[24:25], v[252:253]
	v_pk_fma_f32 v[228:229], v[200:201], v[72:73], v[228:229]
	v_fmac_f32_dpp v218, v72, v180 row_shr:1 row_mask:0xf bank_mask:0xf bound_ctrl:1
	v_fmac_f32_dpp v230, v84, v200 row_shl:1 row_mask:0xf bank_mask:0xf bound_ctrl:1
	v_fmac_f32_dpp v219, v73, v181 row_shr:1 row_mask:0xf bank_mask:0xf bound_ctrl:1
	v_fmac_f32_dpp v231, v85, v201 row_shl:1 row_mask:0xf bank_mask:0xf bound_ctrl:1
	v_pk_mul_f32 v[142:143], v[142:143], v[218:219]
	v_pk_mul_f32 v[178:179], v[178:179], v[252:253]
	v_pk_mul_f32 v[210:211], v[210:211], v[228:229]
	v_pk_mul_f32 v[212:213], v[212:213], v[230:231]
	v_cvt_pk_bf16_f32 v236, v142, v143
	v_cvt_pk_bf16_f32 v240, v178, v179
	v_cvt_pk_bf16_f32 v244, v210, v211
	v_cvt_pk_bf16_f32 v248, v212, v213
	v_pk_fma_f32 v[142:143], v[154:155], v[94:95], v[170:171]
	v_pk_fma_f32 v[178:179], v[154:155], v[38:39], v[170:171]
	v_pk_fma_f32 v[210:211], v[154:155], v[34:35], v[170:171]
	v_pk_fma_f32 v[212:213], v[154:155], v[78:79], v[170:171]
	v_pk_fma_f32 v[142:143], v[162:163], v[38:39], v[142:143]
	v_pk_fma_f32 v[178:179], v[146:147], v[94:95], v[178:179]
	v_pk_fma_f32 v[210:211], v[146:147], v[38:39], v[210:211]
	v_pk_fma_f32 v[212:213], v[146:147], v[34:35], v[212:213]
	v_pk_fma_f32 v[178:179], v[162:163], v[34:35], v[178:179]
	v_pk_fma_f32 v[210:211], v[162:163], v[78:79], v[210:211]
	v_fmac_f32_dpp v142, v78, v146 row_shr:1 row_mask:0xf bank_mask:0xf bound_ctrl:1
	v_fmac_f32_dpp v212, v94, v162 row_shl:1 row_mask:0xf bank_mask:0xf bound_ctrl:1
	v_fmac_f32_dpp v143, v79, v147 row_shr:1 row_mask:0xf bank_mask:0xf bound_ctrl:1
	v_fmac_f32_dpp v213, v95, v163 row_shl:1 row_mask:0xf bank_mask:0xf bound_ctrl:1
; __device__ __forceinline__ unsigned cvt_pk_bf16(float lo, float hi) { unsigned r; asm volatile("v_cvt_pk_bf16_f32 %0, %1, %2" : "=v"(r) : "v"(lo), "v"(hi)); return r; }
; template <int CTRL> __device__ __forceinline__ float dppz(float v) { return __int_as_float(__builtin_amdgcn_update_dpp(0, __float_as_int(v), CTRL, 0xf, 0xf, true)); }
;     __device__ __forceinline__ void operator()(f32x4 (&acc)[2][2][4][2], const Unit& u, int wr, int wc, int fr, int fq, const LAS float* rtab) const {
;     ...
;                     for (int jj = 0; jj < 4; ++jj) {
;                         const float gc = acc[ai][0][m][n][jj], uc = acc[ai][1][m][n][jj];
;                         const float gb = m > 0 ? acc[ai][0][m - 1][n][jj] : 0.f, ga = m < 3 ? acc[ai][0][m + 1][n][jj] : 0.f;
;                         const float ub = m > 0 ? acc[ai][1][m - 1][n][jj] : 0.f, ua = m < 3 ? acc[ai][1][m + 1][n][jj] : 0.f;
;                         const float gp = dppz<0x111>(gc) + dppz<0x10F>(gb), gn = dppz<0x101>(gc) + dppz<0x11F>(ga);
;                         const float up = dppz<0x111>(uc) + dppz<0x10F>(ub), un = dppz<0x101>(uc) + dppz<0x11F>(ua);
;                         const float hg = wg0[jj] * gp + wg1[jj] * gc + wg2[jj] * gn + bg[jj];
;                         const float hu = wu0[jj] * up + wu1[jj] * uc + wu2[jj] * un + bu[jj];
;                         const float sg = __builtin_amdgcn_rcpf(1.f + __builtin_amdgcn_exp2f(-1.4426950408889634f * hg));
;                         y[jj] = hg * sg * hu; }
;                     u32x2 pk; pk.x = cvt_pk_bf16(y[0], y[1]); pk.y = cvt_pk_bf16(y[2], y[3]);
	v_pk_mul_f32 v[218:219], v[142:143], s[54:55] op_sel_hi:[1,0]
	v_pk_mul_f32 v[252:253], v[178:179], s[54:55] op_sel_hi:[1,0]
	v_pk_mul_f32 v[228:229], v[210:211], s[54:55] op_sel_hi:[1,0]
	v_pk_mul_f32 v[230:231], v[212:213], s[54:55] op_sel_hi:[1,0]
	v_exp_f32_e32 v218, v218
	v_exp_f32_e32 v219, v219
	v_exp_f32_e32 v252, v252
	v_exp_f32_e32 v253, v253
	v_exp_f32_e32 v228, v228
	v_exp_f32_e32 v229, v229
	v_exp_f32_e32 v230, v230
	v_exp_f32_e32 v231, v231
	v_pk_add_f32 v[218:219], v[218:219], s[56:57] op_sel_hi:[1,0]
	v_pk_add_f32 v[252:253], v[252:253], s[56:57] op_sel_hi:[1,0]
	v_pk_add_f32 v[228:229], v[228:229], s[56:57] op_sel_hi:[1,0]
	v_pk_add_f32 v[230:231], v[230:231], s[56:57] op_sel_hi:[1,0]
	v_rcp_f32_e32 v218, v218
	v_rcp_f32_e32 v219, v219
	v_rcp_f32_e32 v252, v252
	v_rcp_f32_e32 v253, v253
	v_rcp_f32_e32 v228, v228
	v_rcp_f32_e32 v229, v229
	v_rcp_f32_e32 v230, v230
	v_rcp_f32_e32 v231, v231
	v_pk_mul_f32 v[142:143], v[142:143], v[218:219]
	v_pk_mul_f32 v[178:179], v[178:179], v[252:253]
	v_pk_mul_f32 v[210:211], v[210:211], v[228:229]
	v_pk_mul_f32 v[212:213], v[212:213], v[230:231]
	v_pk_fma_f32 v[218:219], v[190:191], v[86:87], v[222:223]
	v_pk_fma_f32 v[252:253], v[190:191], v[30:31], v[222:223]
	v_pk_fma_f32 v[228:229], v[190:191], v[26:27], v[222:223]
	v_pk_fma_f32 v[230:231], v[190:191], v[74:75], v[222:223]
	v_pk_fma_f32 v[218:219], v[202:203], v[30:31], v[218:219]
	v_pk_fma_f32 v[252:253], v[182:183], v[86:87], v[252:253]
	v_pk_fma_f32 v[228:229], v[182:183], v[30:31], v[228:229]
	v_pk_fma_f32 v[230:231], v[182:183], v[26:27], v[230:231]
	v_pk_fma_f32 v[252:253], v[202:203], v[26:27], v[252:253]
	v_pk_fma_f32 v[228:229], v[202:203], v[74:75], v[228:229]
	v_fmac_f32_dpp v218, v74, v182 row_shr:1 row_mask:0xf bank_mask:0xf bound_ctrl:1
	v_fmac_f32_dpp v230, v86, v202 row_shl:1 row_mask:0xf bank_mask:0xf bound_ctrl:1
	v_fmac_f32_dpp v219, v75, v183 row_shr:1 row_mask:0xf bank_mask:0xf bound_ctrl:1
	v_fmac_f32_dpp v231, v87, v203 row_shl:1 row_mask:0xf bank_mask:0xf bound_ctrl:1
	v_pk_mul_f32 v[142:143], v[142:143], v[218:219]
	v_pk_mul_f32 v[178:179], v[178:179], v[252:253]
	v_pk_mul_f32 v[210:211], v[210:211], v[228:229]
	v_pk_mul_f32 v[212:213], v[212:213], v[230:231]
	v_cvt_pk_bf16_f32 v237, v142, v143
	v_cvt_pk_bf16_f32 v241, v178, v179
	v_cvt_pk_bf16_f32 v245, v210, v211
	v_cvt_pk_bf16_f32 v249, v212, v213
	v_pk_fma_f32 v[142:143], v[156:157], v[88:89], v[172:173]
	v_pk_fma_f32 v[178:179], v[156:157], v[12:13], v[172:173]
	v_pk_fma_f32 v[210:211], v[156:157], v[4:5], v[172:173]
	v_pk_fma_f32 v[212:213], v[156:157], v[56:57], v[172:173]
	v_pk_fma_f32 v[142:143], v[164:165], v[12:13], v[142:143]
	v_pk_fma_f32 v[178:179], v[148:149], v[88:89], v[178:179]
	v_pk_fma_f32 v[210:211], v[148:149], v[12:13], v[210:211]
	v_pk_fma_f32 v[212:213], v[148:149], v[4:5], v[212:213]
	v_pk_fma_f32 v[178:179], v[164:165], v[4:5], v[178:179]
	v_pk_fma_f32 v[210:211], v[164:165], v[56:57], v[210:211]
	v_fmac_f32_dpp v142, v56, v148 row_shr:1 row_mask:0xf bank_mask:0xf bound_ctrl:1
	v_fmac_f32_dpp v212, v88, v164 row_shl:1 row_mask:0xf bank_mask:0xf bound_ctrl:1
	v_fmac_f32_dpp v143, v57, v149 row_shr:1 row_mask:0xf bank_mask:0xf bound_ctrl:1
	v_fmac_f32_dpp v213, v89, v165 row_shl:1 row_mask:0xf bank_mask:0xf bound_ctrl:1
	v_pk_mul_f32 v[218:219], v[142:143], s[54:55] op_sel_hi:[1,0]
	v_pk_mul_f32 v[252:253], v[178:179], s[54:55] op_sel_hi:[1,0]
	v_pk_mul_f32 v[228:229], v[210:211], s[54:55] op_sel_hi:[1,0]
	v_pk_mul_f32 v[230:231], v[212:213], s[54:55] op_sel_hi:[1,0]
	v_exp_f32_e32 v218, v218
	v_exp_f32_e32 v219, v219
	v_exp_f32_e32 v252, v252
	v_exp_f32_e32 v253, v253
	v_exp_f32_e32 v228, v228
	v_exp_f32_e32 v229, v229
	v_exp_f32_e32 v230, v230
	v_exp_f32_e32 v231, v231
	v_pk_add_f32 v[218:219], v[218:219], s[56:57] op_sel_hi:[1,0]
	v_pk_add_f32 v[252:253], v[252:253], s[56:57] op_sel_hi:[1,0]
	v_pk_add_f32 v[228:229], v[228:229], s[56:57] op_sel_hi:[1,0]
	v_pk_add_f32 v[230:231], v[230:231], s[56:57] op_sel_hi:[1,0]
	v_rcp_f32_e32 v218, v218
	v_rcp_f32_e32 v219, v219
	v_rcp_f32_e32 v252, v252
	v_rcp_f32_e32 v253, v253
	v_rcp_f32_e32 v228, v228
	v_rcp_f32_e32 v229, v229
	v_rcp_f32_e32 v230, v230
	v_rcp_f32_e32 v231, v231
	v_pk_mul_f32 v[142:143], v[142:143], v[218:219]
	v_pk_mul_f32 v[178:179], v[178:179], v[252:253]
	v_pk_mul_f32 v[210:211], v[210:211], v[228:229]
	v_pk_mul_f32 v[212:213], v[212:213], v[230:231]
	v_pk_fma_f32 v[218:219], v[196:197], v[80:81], v[224:225]
	v_pk_fma_f32 v[252:253], v[196:197], v[8:9], v[224:225]
	v_pk_fma_f32 v[228:229], v[196:197], v[0:1], v[224:225]
	v_pk_fma_f32 v[230:231], v[196:197], v[40:41], v[224:225]
	v_pk_fma_f32 v[218:219], v[204:205], v[8:9], v[218:219]
	v_pk_fma_f32 v[252:253], v[184:185], v[80:81], v[252:253]
; __device__ __forceinline__ unsigned cvt_pk_bf16(float lo, float hi) { unsigned r; asm volatile("v_cvt_pk_bf16_f32 %0, %1, %2" : "=v"(r) : "v"(lo), "v"(hi)); return r; }
; template <int CTRL> __device__ __forceinline__ float dppz(float v) { return __int_as_float(__builtin_amdgcn_update_dpp(0, __float_as_int(v), CTRL, 0xf, 0xf, true)); }
;     __device__ __forceinline__ void operator()(f32x4 (&acc)[2][2][4][2], const Unit& u, int wr, int wc, int fr, int fq, const LAS float* rtab) const {
;     ...
;                     for (int jj = 0; jj < 4; ++jj) {
;                         const float gc = acc[ai][0][m][n][jj], uc = acc[ai][1][m][n][jj];
;                         const float gb = m > 0 ? acc[ai][0][m - 1][n][jj] : 0.f, ga = m < 3 ? acc[ai][0][m + 1][n][jj] : 0.f;
;                         const float ub = m > 0 ? acc[ai][1][m - 1][n][jj] : 0.f, ua = m < 3 ? acc[ai][1][m + 1][n][jj] : 0.f;
;                         const float gp = dppz<0x111>(gc) + dppz<0x10F>(gb), gn = dppz<0x101>(gc) + dppz<0x11F>(ga);
;                         const float up = dppz<0x111>(uc) + dppz<0x10F>(ub), un = dppz<0x101>(uc) + dppz<0x11F>(ua);
;                         const float hg = wg0[jj] * gp + wg1[jj] * gc + wg2[jj] * gn + bg[jj];
;                         const float hu = wu0[jj] * up + wu1[jj] * uc + wu2[jj] * un + bu[jj];
;                         const float sg = __builtin_amdgcn_rcpf(1.f + __builtin_amdgcn_exp2f(-1.4426950408889634f * hg));
;                         y[jj] = hg * sg * hu; }
;                     u32x2 pk; pk.x = cvt_pk_bf16(y[0], y[1]); pk.y = cvt_pk_bf16(y[2], y[3]);
;                     if (n == 0) ypk[ai][m] = pk;
;                     else {
;                         const bool deferred = (m == 0 && fr == 0) || (m == 3 && fr == 15);
;                         if (!deferred) { u32x4 w; w.x = ypk[ai][m].x; w.y = ypk[ai][m].y; w.z = pk.x; w.w = pk.y; *(u32x4*)(act + (size_t)(r64 + m * 16 + fr) * DFF + c0) = w; } }
	v_pk_fma_f32 v[228:229], v[184:185], v[8:9], v[228:229]
	v_pk_fma_f32 v[230:231], v[184:185], v[0:1], v[230:231]
	v_pk_fma_f32 v[252:253], v[204:205], v[0:1], v[252:253]
	v_pk_fma_f32 v[228:229], v[204:205], v[40:41], v[228:229]
	v_fmac_f32_dpp v218, v40, v184 row_shr:1 row_mask:0xf bank_mask:0xf bound_ctrl:1
	v_fmac_f32_dpp v230, v80, v204 row_shl:1 row_mask:0xf bank_mask:0xf bound_ctrl:1
	v_fmac_f32_dpp v219, v41, v185 row_shr:1 row_mask:0xf bank_mask:0xf bound_ctrl:1
	v_fmac_f32_dpp v231, v81, v205 row_shl:1 row_mask:0xf bank_mask:0xf bound_ctrl:1
	v_pk_mul_f32 v[142:143], v[142:143], v[218:219]
	v_pk_mul_f32 v[178:179], v[178:179], v[252:253]
	v_pk_mul_f32 v[210:211], v[210:211], v[228:229]
	v_pk_mul_f32 v[212:213], v[212:213], v[230:231]
	v_cvt_pk_bf16_f32 v238, v142, v143
	v_cvt_pk_bf16_f32 v242, v178, v179
	v_cvt_pk_bf16_f32 v246, v210, v211
	v_cvt_pk_bf16_f32 v250, v212, v213
	v_pk_fma_f32 v[142:143], v[158:159], v[90:91], v[174:175]
	v_pk_fma_f32 v[178:179], v[158:159], v[14:15], v[174:175]
	v_pk_fma_f32 v[210:211], v[158:159], v[6:7], v[174:175]
	v_pk_fma_f32 v[212:213], v[158:159], v[58:59], v[174:175]
	v_pk_fma_f32 v[142:143], v[166:167], v[14:15], v[142:143]
	v_pk_fma_f32 v[178:179], v[150:151], v[90:91], v[178:179]
	v_pk_fma_f32 v[210:211], v[150:151], v[14:15], v[210:211]
	v_pk_fma_f32 v[212:213], v[150:151], v[6:7], v[212:213]
	v_pk_fma_f32 v[178:179], v[166:167], v[6:7], v[178:179]
	v_pk_fma_f32 v[210:211], v[166:167], v[58:59], v[210:211]
	v_fmac_f32_dpp v142, v58, v150 row_shr:1 row_mask:0xf bank_mask:0xf bound_ctrl:1
	v_fmac_f32_dpp v212, v90, v166 row_shl:1 row_mask:0xf bank_mask:0xf bound_ctrl:1
	v_fmac_f32_dpp v143, v59, v151 row_shr:1 row_mask:0xf bank_mask:0xf bound_ctrl:1
	v_fmac_f32_dpp v213, v91, v167 row_shl:1 row_mask:0xf bank_mask:0xf bound_ctrl:1
	v_pk_mul_f32 v[218:219], v[142:143], s[54:55] op_sel_hi:[1,0]
	v_pk_mul_f32 v[252:253], v[178:179], s[54:55] op_sel_hi:[1,0]
	v_pk_mul_f32 v[228:229], v[210:211], s[54:55] op_sel_hi:[1,0]
	v_pk_mul_f32 v[230:231], v[212:213], s[54:55] op_sel_hi:[1,0]
	v_exp_f32_e32 v218, v218
	v_exp_f32_e32 v219, v219
	v_exp_f32_e32 v252, v252
	v_exp_f32_e32 v253, v253
	v_exp_f32_e32 v228, v228
	v_exp_f32_e32 v229, v229
	v_exp_f32_e32 v230, v230
	v_exp_f32_e32 v231, v231
	v_pk_add_f32 v[218:219], v[218:219], s[56:57] op_sel_hi:[1,0]
	v_pk_add_f32 v[252:253], v[252:253], s[56:57] op_sel_hi:[1,0]
	v_pk_add_f32 v[228:229], v[228:229], s[56:57] op_sel_hi:[1,0]
	v_pk_add_f32 v[230:231], v[230:231], s[56:57] op_sel_hi:[1,0]
	v_rcp_f32_e32 v218, v218
	v_rcp_f32_e32 v219, v219
	v_rcp_f32_e32 v252, v252
	v_rcp_f32_e32 v253, v253
	v_rcp_f32_e32 v228, v228
	v_rcp_f32_e32 v229, v229
	v_rcp_f32_e32 v230, v230
	v_rcp_f32_e32 v231, v231
	v_pk_mul_f32 v[142:143], v[142:143], v[218:219]
	v_pk_mul_f32 v[178:179], v[178:179], v[252:253]
	v_pk_mul_f32 v[210:211], v[210:211], v[228:229]
	v_pk_mul_f32 v[212:213], v[212:213], v[230:231]
	v_pk_fma_f32 v[218:219], v[198:199], v[82:83], v[226:227]
	v_pk_fma_f32 v[252:253], v[198:199], v[10:11], v[226:227]
	v_pk_fma_f32 v[228:229], v[198:199], v[2:3], v[226:227]
	v_pk_fma_f32 v[230:231], v[198:199], v[42:43], v[226:227]
	v_pk_fma_f32 v[218:219], v[206:207], v[10:11], v[218:219]
	v_pk_fma_f32 v[252:253], v[186:187], v[82:83], v[252:253]
	v_pk_fma_f32 v[228:229], v[186:187], v[10:11], v[228:229]
	v_pk_fma_f32 v[230:231], v[186:187], v[2:3], v[230:231]
	v_pk_fma_f32 v[252:253], v[206:207], v[2:3], v[252:253]
	v_pk_fma_f32 v[228:229], v[206:207], v[42:43], v[228:229]
	v_fmac_f32_dpp v218, v42, v186 row_shr:1 row_mask:0xf bank_mask:0xf bound_ctrl:1
	v_fmac_f32_dpp v230, v82, v206 row_shl:1 row_mask:0xf bank_mask:0xf bound_ctrl:1
	v_fmac_f32_dpp v219, v43, v187 row_shr:1 row_mask:0xf bank_mask:0xf bound_ctrl:1
	v_fmac_f32_dpp v231, v83, v207 row_shl:1 row_mask:0xf bank_mask:0xf bound_ctrl:1
	v_pk_mul_f32 v[142:143], v[142:143], v[218:219]
	v_pk_mul_f32 v[178:179], v[178:179], v[252:253]
	v_pk_mul_f32 v[210:211], v[210:211], v[228:229]
	v_pk_mul_f32 v[212:213], v[212:213], v[230:231]
	v_cvt_pk_bf16_f32 v239, v142, v143
	v_cvt_pk_bf16_f32 v243, v178, v179
	v_cvt_pk_bf16_f32 v247, v210, v211
	v_cvt_pk_bf16_f32 v251, v212, v213
	s_add_u32 s58, s28, 0x160000
	s_addc_u32 s59, s29, 0
	s_mov_b64 exec, s[12:13]
	global_store_dwordx4 v234, v[236:239], s[58:59]
	s_mov_b64 exec, -1
	s_add_u32 s58, s28, 0x162c00
	s_addc_u32 s59, s29, 0
	global_store_dwordx4 v234, v[240:243], s[58:59]
	s_add_u32 s58, s28, 0x165800
	s_addc_u32 s59, s29, 0
	global_store_dwordx4 v234, v[244:247], s[58:59]
	s_add_u32 s58, s28, 0x168400
	s_addc_u32 s59, s29, 0
	s_mov_b64 exec, s[10:11]
	global_store_dwordx4 v234, v[248:251], s[58:59]
	s_mov_b64 exec, -1
	s_andn2_b64 vcc, exec, s[52:53]
	s_mov_b64 s[52:53], -1
	s_cbranch_vccnz .LBB0_834
